# post phase 8: SBON loads prefetched 2-deep, counted vmcnt instead of vmcnt(0) per token group
# speedup vs baseline: 1.0199x; 1.0035x over previous
; __device__ __forceinline__ float bf2f(bf16_t b) { return __uint_as_float(((unsigned)b) << 16); }
; __device__ __forceinline__ void post_phase(PREF p, char* smem, const int wid_u, const int tile_first, const int tile_end, const int tile_step) {
;     ...
;     __syncthreads();
;     f32x4 acc[2][4] = {};
; #pragma unroll
;     for (int ks = 0; ks < 6; ++ks) {
;       bf16x8 a[2];
; #pragma unroll
;       for (int mt = 0; mt < 2; ++mt) a[mt] = *reinterpret_cast<const bf16x8*>(Ag + (mt * 16 + fr) * 200 + ks * 32 + fq * 8);
; #pragma unroll
;       for (int mt = 0; mt < 2; ++mt)
; #pragma unroll
;         for (int nt = 0; nt < 4; ++nt) acc[mt][nt] = __builtin_amdgcn_mfma_f32_16x16x32_bf16(a[mt], Bg[nt][ks], acc[mt][nt], 0, 0, 0);
;     }
; #pragma unroll
;     for (int mt = 0; mt < 2; ++mt)
; #pragma unroll
;       for (int jj = 0; jj < 4; ++jj) {
;         const int tok = mt * 16 + fq * 4 + jj, row = row0 + tok;
;         float yv[4], sm_ = 0.f;
; #pragma unroll
;         for (int nt = 0; nt < 4; ++nt) { yv[nt] = ys[tok * 516 + w * 64 + nt * 16 + fr]; sm_ += yv[nt]; }
;         const float mean = row16_sum(sm_) * (1.f / 64.f);
;         float vs = 0.f;
; #pragma unroll
;         for (int nt = 0; nt < 4; ++nt) { yv[nt] -= mean; vs += yv[nt] * yv[nt]; }
;         const float rs = rsqrtf(row16_sum(vs) * (1.f / 64.f) + 64e-5f);
;         const float2 sb2 = *(const float2*)(P_SBON + ((size_t)row * 8 + w) * 2);
;         const float sbs = sb2.x + sb2.y;
; #pragma unroll
;         for (int nt = 0; nt < 4; ++nt) {
;           const float vv = bf2f(vt[tok * 520 + w * 64 + nt * 16 + fr]);
;           const float o = (yv[nt] * rs * lng[nt] + lnb[nt] + sbs * vv) * acc[mt][nt][jj];
.LBB0_826:
	s_waitcnt lgkmcnt(0)
	s_barrier
	ds_read_b128 v[80:83], v157
	ds_read_b128 v[84:87], v157 offset:64
	v_or_b32_e32 v138, s39, v149
	v_ashrrev_i32_e32 v139, 31, v138
	s_waitcnt lgkmcnt(1)
	v_mfma_f32_16x16x32_bf16 v[88:91], v[80:83], v[76:79], 0
	v_add_u32_e32 v120, 0xb400, v158
	v_add_u32_e32 v166, 0xb400, v160
	v_mfma_f32_16x16x32_bf16 v[92:95], v[80:83], v[56:59], 0
	v_mfma_f32_16x16x32_bf16 v[96:99], v[80:83], v[36:39], 0
	v_mfma_f32_16x16x32_bf16 v[100:103], v[80:83], v[16:19], 0
	v_lshlrev_b64 v[80:81], 6, v[138:139]
	v_lshl_add_u64 v[80:81], v[130:131], 0, v[80:81]
	global_load_dwordx2 v[140:141], v[80:81], off
	v_mov_b32_e32 v250, v80
	v_mov_b32_e32 v251, v81
	global_load_dwordx2 v[252:253], v[80:81], off offset:64
	global_load_dwordx2 v[254:255], v[80:81], off offset:128
	s_waitcnt lgkmcnt(0)
	v_mfma_f32_16x16x32_bf16 v[88:91], v[84:87], v[72:75], v[88:91]
	ds_read_b128 v[104:107], v157 offset:128
	ds_read_b128 v[108:111], v157 offset:192
	ds_read_b128 v[112:115], v157 offset:256
	ds_read_b128 v[116:119], v157 offset:320
	v_mov_b64_e32 v[82:83], s[6:7]
	v_mfma_f32_16x16x32_bf16 v[92:95], v[84:87], v[52:55], v[92:95]
	v_mov_b64_e32 v[80:81], s[4:5]
	v_lshlrev_b64 v[138:139], 11, v[138:139]
	v_lshl_add_u64 v[138:139], v[132:133], 0, v[138:139]
	v_mfma_f32_16x16x32_bf16 v[96:99], v[84:87], v[32:35], v[96:99]
	s_waitcnt vmcnt(2)
	v_add_f32_e32 v140, v140, v141
	v_mfma_f32_16x16x32_bf16 v[84:87], v[84:87], v[12:15], v[100:103]
	ds_read_u16 v168, v159 offset:12800
	ds_read_u16 v169, v159 offset:12832
	ds_read_u16 v170, v159 offset:12864
	ds_read_u16 v171, v159 offset:12896
	ds_read_u16 v172, v161 offset:12800
	ds_read_u16 v173, v161 offset:12832
	ds_read_u16 v174, v161 offset:12864
	ds_read_u16 v175, v161 offset:12896
	ds_read2_b32 v[100:101], v120 offset1:16
	ds_read2_b32 v[102:103], v120 offset0:32 offset1:48
	ds_read2_b32 v[164:165], v166 offset1:16
	ds_read2_b32 v[166:167], v166 offset0:32 offset1:48
	s_waitcnt lgkmcnt(10)
	v_lshlrev_b32_e32 v176, 16, v169
	v_mfma_f32_16x16x32_bf16 v[88:91], v[104:107], v[68:71], v[88:91]
	s_waitcnt lgkmcnt(2)
	v_mov_b32_e32 v169, v102
	v_add_f32_e32 v177, 0, v100
	v_lshlrev_b32_e32 v120, 16, v168
	v_mfma_f32_16x16x32_bf16 v[92:95], v[104:107], v[48:51], v[92:95]
	v_mov_b32_e32 v168, v103
	v_mfma_f32_16x16x32_bf16 v[96:99], v[104:107], v[28:31], v[96:99]
	v_mfma_f32_16x16x32_bf16 v[84:87], v[104:107], v[8:11], v[84:87]
	s_waitcnt lgkmcnt(1)
	v_add_f32_e32 v104, 0, v164
	v_add_f32_e32 v105, v177, v101
	v_add_f32_e32 v104, v104, v165
	v_add_f32_e32 v102, v105, v102
	s_waitcnt lgkmcnt(0)
	v_add_f32_e32 v104, v104, v166
	v_mfma_f32_16x16x32_bf16 v[88:91], v[108:111], v[64:67], v[88:91]
	v_add_f32_e32 v102, v102, v103
	v_add_f32_e32 v103, v104, v167
	v_mov_b32_e32 v106, v167
	v_mfma_f32_16x16x32_bf16 v[92:95], v[108:111], v[44:47], v[92:95]
	v_add_f32_dpp v102, v102, v102 row_ror:8 row_mask:0xf bank_mask:0xf bound_ctrl:1
	v_add_f32_dpp v103, v103, v103 row_ror:8 row_mask:0xf bank_mask:0xf bound_ctrl:1
	v_mov_b32_e32 v107, v166
	v_mfma_f32_16x16x32_bf16 v[96:99], v[108:111], v[24:27], v[96:99]
	v_add_f32_dpp v102, v102, v102 row_ror:4 row_mask:0xf bank_mask:0xf bound_ctrl:1
	v_add_f32_dpp v103, v103, v103 row_ror:4 row_mask:0xf bank_mask:0xf bound_ctrl:1
	v_mfma_f32_16x16x32_bf16 v[84:87], v[108:111], v[4:7], v[84:87]
	v_add_f32_dpp v102, v102, v102 row_ror:2 row_mask:0xf bank_mask:0xf bound_ctrl:1
	v_add_f32_dpp v103, v103, v103 row_ror:2 row_mask:0xf bank_mask:0xf bound_ctrl:1
	v_mfma_f32_16x16x32_bf16 v[88:91], v[112:115], v[60:63], v[88:91]
	v_add_f32_dpp v102, v102, v102 row_ror:1 row_mask:0xf bank_mask:0xf bound_ctrl:1
	v_add_f32_dpp v103, v103, v103 row_ror:1 row_mask:0xf bank_mask:0xf bound_ctrl:1
	v_mul_f32_e32 v108, 0x3c800000, v102
	v_mfma_f32_16x16x32_bf16 v[92:95], v[112:115], v[40:43], v[92:95]
	v_mul_f32_e32 v110, 0x3c800000, v103
	v_pk_add_f32 v[166:167], v[100:101], v[108:109] op_sel_hi:[1,0] neg_lo:[0,1] neg_hi:[0,1]
	v_pk_add_f32 v[164:165], v[164:165], v[110:111] op_sel_hi:[1,0] neg_lo:[0,1] neg_hi:[0,1]
	v_mfma_f32_16x16x32_bf16 v[102:105], v[112:115], v[20:23], v[96:99]
	v_pk_add_f32 v[108:109], v[168:169], v[108:109] op_sel_hi:[1,0] neg_lo:[0,1] neg_hi:[0,1]
	v_pk_add_f32 v[110:111], v[106:107], v[110:111] op_sel_hi:[1,0] neg_lo:[0,1] neg_hi:[0,1]
	v_pk_mul_f32 v[106:107], v[166:167], v[166:167]
	v_mfma_f32_16x16x32_bf16 v[84:87], v[112:115], v[0:3], v[84:87]
	v_mul_f32_e64 v114, v164, v164
	v_mul_f32_e64 v115, v165, v165
	v_pk_mul_f32 v[112:113], v[108:109], v[108:109]
	v_pk_mul_f32 v[168:169], v[110:111], v[110:111]
	v_mfma_f32_16x16x32_bf16 v[98:101], v[116:119], v[80:83], v[88:91]
	s_nop 2
	v_mov_b32_e32 v88, v114
	v_mov_b32_e32 v89, v106
	v_mov_b32_e32 v106, v115
	v_mfma_f32_16x16x32_bf16 v[94:97], v[116:119], v[80:83], v[92:95]
	v_add_f32_e64 v88, v88, v106
	v_add_f32_e64 v89, v89, v107
	v_mov_b64_e32 v[106:107], s[18:19]
	v_mfma_f32_16x16x32_bf16 v[90:93], v[116:119], v[80:83], v[102:105]
	s_nop 2
	v_mov_b32_e32 v102, v169
	v_mov_b32_e32 v103, v113
	v_pk_add_f32 v[102:103], v[102:103], v[88:89]
	v_mov_b32_e32 v169, v112
	v_mfma_f32_16x16x32_bf16 v[86:89], v[116:119], v[80:83], v[84:87]
	v_lshlrev_b32_e32 v104, 16, v171
	v_add_u32_e32 v116, 0xbc00, v160
	s_nop 0
	v_pk_add_f32 v[84:85], v[168:169], v[102:103]
	v_mov_b32_e32 v103, v121
	v_mov_b32_e32 v102, v121
	s_nop 0
	v_mov_b32_dpp v103, v85 row_ror:8 row_mask:0xf bank_mask:0xf
	v_mov_b32_dpp v102, v84 row_ror:8 row_mask:0xf bank_mask:0xf
	v_pk_add_f32 v[84:85], v[84:85], v[102:103]
	v_mov_b32_e32 v103, v121
	v_mov_b32_e32 v102, v121
	s_nop 0
	v_mov_b32_dpp v103, v85 row_ror:4 row_mask:0xf bank_mask:0xf
; __device__ __forceinline__ float bf2f(bf16_t b) { return __uint_as_float(((unsigned)b) << 16); }
; __device__ __forceinline__ void post_phase(PREF p, char* smem, const int wid_u, const int tile_first, const int tile_end, const int tile_step) {
;     ...
; #pragma unroll
;     for (int mt = 0; mt < 2; ++mt)
; #pragma unroll
;       for (int jj = 0; jj < 4; ++jj) {
;         const int tok = mt * 16 + fq * 4 + jj, row = row0 + tok;
;         float yv[4], sm_ = 0.f;
; #pragma unroll
;         for (int nt = 0; nt < 4; ++nt) { yv[nt] = ys[tok * 516 + w * 64 + nt * 16 + fr]; sm_ += yv[nt]; }
;         const float mean = row16_sum(sm_) * (1.f / 64.f);
;         float vs = 0.f;
; #pragma unroll
;         for (int nt = 0; nt < 4; ++nt) { yv[nt] -= mean; vs += yv[nt] * yv[nt]; }
;         const float rs = rsqrtf(row16_sum(vs) * (1.f / 64.f) + 64e-5f);
;         const float2 sb2 = *(const float2*)(P_SBON + ((size_t)row * 8 + w) * 2);
;         const float sbs = sb2.x + sb2.y;
; #pragma unroll
;         for (int nt = 0; nt < 4; ++nt) {
;           const float vv = bf2f(vt[tok * 520 + w * 64 + nt * 16 + fr]);
;           const float o = (yv[nt] * rs * lng[nt] + lnb[nt] + sbs * vv) * acc[mt][nt][jj];
;           mo[(size_t)row * D + 512 + w * 64 + nt * 16 + fr] = (bf16_t)(cvt_pk_bf16(o, 0.f) & 0xffff);
;         }
;       }
	v_mov_b32_dpp v102, v84 row_ror:4 row_mask:0xf bank_mask:0xf
	v_pk_add_f32 v[84:85], v[84:85], v[102:103]
	v_mov_b32_e32 v103, v121
	v_mov_b32_e32 v102, v121
	s_nop 0
	v_mov_b32_dpp v103, v85 row_ror:2 row_mask:0xf bank_mask:0xf
	v_mov_b32_dpp v102, v84 row_ror:2 row_mask:0xf bank_mask:0xf
	v_pk_add_f32 v[84:85], v[84:85], v[102:103]
	v_mov_b32_e32 v103, v121
	v_mov_b32_e32 v102, v121
	s_nop 0
	v_mov_b32_dpp v103, v85 row_ror:1 row_mask:0xf bank_mask:0xf
	v_mov_b32_dpp v102, v84 row_ror:1 row_mask:0xf bank_mask:0xf
	v_pk_add_f32 v[84:85], v[84:85], v[102:103]
	v_lshlrev_b32_e32 v103, 16, v170
	v_pk_fma_f32 v[84:85], v[84:85], s[16:17], v[106:107] op_sel_hi:[1,0,0]
	s_nop 0
	v_mul_f32_e32 v102, 0x4b800000, v85
	v_cmp_gt_f32_e32 vcc, s38, v85
	s_nop 1
	v_cndmask_b32_e32 v85, v85, v102, vcc
	v_rsq_f32_e32 v85, v85
	v_or_b32_e32 v102, s39, v150
	v_mul_f32_e32 v105, 0x45800000, v85
	v_cndmask_b32_e32 v85, v85, v105, vcc
	v_mul_f32_e32 v105, v166, v85
	v_fma_f32 v105, v129, v105, v145
	v_fmac_f32_e32 v105, v140, v120
	v_mul_f32_e32 v98, v98, v105
	v_cvt_pk_bf16_f32 v98, v98, s0
	global_store_short v[138:139], v98, off
	v_mul_f32_e32 v98, v167, v85
	v_fma_f32 v98, v142, v98, v146
	v_fmac_f32_e32 v98, v140, v176
	v_mul_f32_e32 v94, v94, v98
	v_cvt_pk_bf16_f32 v94, v94, s0
	global_store_short v[138:139], v94, off offset:32
	v_mul_f32_e32 v94, v109, v85
	v_mul_f32_e32 v85, v108, v85
	v_fma_f32 v94, v143, v94, v147
	v_fma_f32 v85, v144, v85, v148
	v_fmac_f32_e32 v94, v140, v103
	v_fmac_f32_e32 v85, v140, v104
	v_mul_f32_e32 v90, v90, v94
	v_mul_f32_e32 v85, v86, v85
	v_ashrrev_i32_e32 v103, 31, v102
	v_cvt_pk_bf16_f32 v90, v90, s0
	v_cvt_pk_bf16_f32 v85, v85, s0
	v_lshlrev_b64 v[104:105], 6, v[102:103]
	global_store_short v[138:139], v90, off offset:64
	global_store_short v[138:139], v85, off offset:96
	v_lshl_add_u64 v[104:105], v[130:131], 0, v[104:105]
	v_mul_f32_e32 v85, 0x4b800000, v84
	v_cmp_gt_f32_e32 vcc, s38, v84
	v_lshlrev_b64 v[102:103], 11, v[102:103]
	v_lshlrev_b32_e32 v90, 16, v172
	v_cndmask_b32_e32 v84, v84, v85, vcc
	v_rsq_f32_e32 v86, v84
	v_lshl_add_u64 v[84:85], v[132:133], 0, v[102:103]
	v_lshlrev_b32_e32 v94, 16, v173
	v_add_u32_e32 v120, 0xc400, v160
	v_mul_f32_e32 v98, 0x45800000, v86
	v_cndmask_b32_e32 v86, v86, v98, vcc
	v_mul_f32_e32 v98, v164, v86
	v_fma_f32 v98, v129, v98, v145
	v_mul_f32_e32 v102, v165, v86
	s_waitcnt vmcnt(5)
	v_add_f32_e32 v103, v252, v253
	global_load_dwordx2 v[252:253], v[250:251], off offset:192
	v_fmac_f32_e32 v98, v103, v90
	v_mul_f32_e32 v90, v99, v98
	v_cvt_pk_bf16_f32 v90, v90, s0
	global_store_short v[84:85], v90, off
	v_fma_f32 v90, v142, v102, v146
	v_fmac_f32_e32 v90, v103, v94
	v_mul_f32_e32 v90, v95, v90
	v_cvt_pk_bf16_f32 v90, v90, s0
	v_mul_f32_e32 v94, v111, v86
	global_store_short v[84:85], v90, off offset:32
	v_lshlrev_b32_e32 v90, 16, v174
	v_fma_f32 v94, v143, v94, v147
	v_fmac_f32_e32 v94, v103, v90
	v_mul_f32_e32 v90, v91, v94
	v_cvt_pk_bf16_f32 v90, v90, s0
	v_mul_f32_e32 v86, v110, v86
	global_store_short v[84:85], v90, off offset:64
	v_lshlrev_b32_e32 v90, 16, v175
	v_fma_f32 v86, v144, v86, v148
	v_fmac_f32_e32 v86, v103, v90
	v_mul_f32_e32 v86, v87, v86
	v_or_b32_e32 v90, s39, v151
	v_cvt_pk_bf16_f32 v86, v86, s0
	v_ashrrev_i32_e32 v91, 31, v90
	global_store_short v[84:85], v86, off offset:96
	v_lshlrev_b64 v[84:85], 6, v[90:91]
	v_lshl_add_u64 v[84:85], v[130:131], 0, v[84:85]
	ds_read_b128 v[108:111], v157 offset:6400
	ds_read_b128 v[112:115], v157 offset:6464
	ds_read_b128 v[102:105], v157 offset:6528
	ds_read_b128 v[84:87], v157 offset:6592
	ds_read_u16 v164, v161 offset:13840
	ds_read_u16 v165, v161 offset:13872
	ds_read_u16 v180, v161 offset:13904
	ds_read_u16 v181, v161 offset:13936
	ds_read_u16 v182, v161 offset:14880
	ds_read_u16 v183, v161 offset:14912
	ds_read_u16 v184, v161 offset:14944
	ds_read_u16 v185, v161 offset:14976
	ds_read2_b32 v[98:99], v116 offset0:4 offset1:20
	ds_read2_b32 v[168:169], v116 offset0:36 offset1:52
	ds_read2_b32 v[170:171], v120 offset0:8 offset1:24
	ds_read2_b32 v[172:173], v120 offset0:40 offset1:56
	s_waitcnt lgkmcnt(14)
	v_mfma_f32_16x16x32_bf16 v[116:119], v[108:111], v[76:79], 0
	s_waitcnt lgkmcnt(3)
	v_add_f32_e32 v120, 0, v98
	v_add_f32_e32 v120, v120, v99
	s_waitcnt lgkmcnt(1)
	v_add_f32_e32 v176, 0, v170
	v_mfma_f32_16x16x32_bf16 v[138:141], v[108:111], v[56:59], 0
	v_add_f32_e32 v176, v176, v171
	v_mov_b32_e32 v175, v168
	v_add_f32_e32 v120, v120, v168
	s_waitcnt lgkmcnt(0)
	v_add_f32_e32 v168, v176, v172
	v_lshlrev_b32_e32 v186, 16, v164
	v_lshlrev_b32_e32 v187, 16, v165
	v_mfma_f32_16x16x32_bf16 v[164:167], v[108:111], v[36:39], 0
	v_add_f32_e32 v120, v120, v169
	v_add_f32_e32 v168, v168, v173
	v_mov_b32_e32 v174, v169
	v_mfma_f32_16x16x32_bf16 v[108:111], v[108:111], v[16:19], 0
	v_add_f32_dpp v120, v120, v120 row_ror:8 row_mask:0xf bank_mask:0xf bound_ctrl:1
	v_add_f32_dpp v168, v168, v168 row_ror:8 row_mask:0xf bank_mask:0xf bound_ctrl:1
	v_lshlrev_b64 v[90:91], 11, v[90:91]
	v_mfma_f32_16x16x32_bf16 v[116:119], v[112:115], v[72:75], v[116:119]
	v_add_f32_dpp v120, v120, v120 row_ror:4 row_mask:0xf bank_mask:0xf bound_ctrl:1
	v_add_f32_dpp v168, v168, v168 row_ror:4 row_mask:0xf bank_mask:0xf bound_ctrl:1
	v_lshl_add_u64 v[90:91], v[132:133], 0, v[90:91]
	v_mfma_f32_16x16x32_bf16 v[138:141], v[112:115], v[52:55], v[138:141]
	v_add_f32_dpp v120, v120, v120 row_ror:2 row_mask:0xf bank_mask:0xf bound_ctrl:1
	v_add_f32_dpp v168, v168, v168 row_ror:2 row_mask:0xf bank_mask:0xf bound_ctrl:1
	v_mfma_f32_16x16x32_bf16 v[164:167], v[112:115], v[32:35], v[164:167]
	v_mfma_f32_16x16x32_bf16 v[108:111], v[112:115], v[12:15], v[108:111]
	v_add_f32_dpp v112, v120, v120 row_ror:1 row_mask:0xf bank_mask:0xf bound_ctrl:1
	v_add_f32_dpp v113, v168, v168 row_ror:1 row_mask:0xf bank_mask:0xf bound_ctrl:1
	v_mul_f32_e32 v120, 0x3c800000, v112
	v_mul_f32_e32 v168, 0x3c800000, v113
	v_pk_add_f32 v[98:99], v[98:99], v[120:121] op_sel_hi:[1,0] neg_lo:[0,1] neg_hi:[0,1]
	v_mfma_f32_16x16x32_bf16 v[112:115], v[102:105], v[68:71], v[116:119]
	v_add_f32_e64 v174, v174, -v120
	v_add_f32_e64 v175, v175, -v120
	v_pk_mul_f32 v[176:177], v[98:99], v[98:99]
	v_pk_mul_f32 v[178:179], v[174:175], v[174:175]
	v_mfma_f32_16x16x32_bf16 v[116:119], v[102:105], v[48:51], v[138:141]
	s_waitcnt vmcnt(9)
; __device__ __forceinline__ float bf2f(bf16_t b) { return __uint_as_float(((unsigned)b) << 16); }
; __device__ __forceinline__ void post_phase(PREF p, char* smem, const int wid_u, const int tile_first, const int tile_end, const int tile_step) {
;     ...
; #pragma unroll
;     for (int mt = 0; mt < 2; ++mt)
; #pragma unroll
;       for (int jj = 0; jj < 4; ++jj) {
;         const int tok = mt * 16 + fq * 4 + jj, row = row0 + tok;
;         float yv[4], sm_ = 0.f;
; #pragma unroll
;         for (int nt = 0; nt < 4; ++nt) { yv[nt] = ys[tok * 516 + w * 64 + nt * 16 + fr]; sm_ += yv[nt]; }
;         const float mean = row16_sum(sm_) * (1.f / 64.f);
;         float vs = 0.f;
; #pragma unroll
;         for (int nt = 0; nt < 4; ++nt) { yv[nt] -= mean; vs += yv[nt] * yv[nt]; }
;         const float rs = rsqrtf(row16_sum(vs) * (1.f / 64.f) + 64e-5f);
;         const float2 sb2 = *(const float2*)(P_SBON + ((size_t)row * 8 + w) * 2);
;         const float sbs = sb2.x + sb2.y;
; #pragma unroll
;         for (int nt = 0; nt < 4; ++nt) {
;           const float vv = bf2f(vt[tok * 520 + w * 64 + nt * 16 + fr]);
;           const float o = (yv[nt] * rs * lng[nt] + lnb[nt] + sbs * vv) * acc[mt][nt][jj];
;           mo[(size_t)row * D + 512 + w * 64 + nt * 16 + fr] = (bf16_t)(cvt_pk_bf16(o, 0.f) & 0xffff);
;         }
;       }
	v_add_f32_e32 v120, v254, v255
	global_load_dwordx2 v[254:255], v[250:251], off offset:1024
	v_pk_add_f32 v[94:95], v[170:171], v[168:169] op_sel_hi:[1,0] neg_lo:[0,1] neg_hi:[0,1]
	v_mov_b32_e32 v140, v173
	v_mov_b32_e32 v141, v172
	v_pk_mul_f32 v[138:139], v[94:95], v[94:95]
	v_pk_add_f32 v[168:169], v[140:141], v[168:169] op_sel_hi:[1,0] neg_lo:[0,1] neg_hi:[0,1]
	v_mov_b32_e32 v170, v138
	v_pk_mul_f32 v[140:141], v[168:169], v[168:169]
	v_mov_b32_e32 v171, v176
	v_mov_b32_e32 v176, v139
	v_pk_add_f32 v[138:139], v[170:171], v[176:177]
	v_mov_b32_e32 v170, v141
	v_mov_b32_e32 v171, v179
	v_pk_add_f32 v[138:139], v[170:171], v[138:139]
	v_mov_b32_e32 v141, v178
	v_pk_add_f32 v[138:139], v[140:141], v[138:139]
	v_mov_b32_e32 v141, v121
	v_mov_b32_e32 v140, v121
	s_nop 0
	v_mov_b32_dpp v141, v139 row_ror:8 row_mask:0xf bank_mask:0xf
	v_mov_b32_dpp v140, v138 row_ror:8 row_mask:0xf bank_mask:0xf
	v_pk_add_f32 v[138:139], v[138:139], v[140:141]
	v_mov_b32_e32 v141, v121
	v_mov_b32_e32 v140, v121
	s_nop 0
	v_mov_b32_dpp v141, v139 row_ror:4 row_mask:0xf bank_mask:0xf
	v_mov_b32_dpp v140, v138 row_ror:4 row_mask:0xf bank_mask:0xf
	v_pk_add_f32 v[138:139], v[138:139], v[140:141]
	v_mov_b32_e32 v141, v121
	v_mov_b32_e32 v140, v121
	s_nop 0
	v_mov_b32_dpp v141, v139 row_ror:2 row_mask:0xf bank_mask:0xf
	v_mov_b32_dpp v140, v138 row_ror:2 row_mask:0xf bank_mask:0xf
	v_pk_add_f32 v[138:139], v[138:139], v[140:141]
	v_mov_b32_e32 v141, v121
	v_mov_b32_e32 v140, v121
	s_nop 0
	v_mov_b32_dpp v141, v139 row_ror:1 row_mask:0xf bank_mask:0xf
	v_mov_b32_dpp v140, v138 row_ror:1 row_mask:0xf bank_mask:0xf
	v_pk_add_f32 v[138:139], v[138:139], v[140:141]
	v_lshlrev_b32_e32 v140, 16, v180
	v_pk_fma_f32 v[170:171], v[138:139], s[16:17], v[106:107] op_sel_hi:[1,0,0]
	v_lshlrev_b32_e32 v141, 16, v181
	v_mul_f32_e32 v138, 0x4b800000, v171
	v_cmp_gt_f32_e32 vcc, s38, v171
	s_nop 1
	v_cndmask_b32_e32 v138, v171, v138, vcc
	v_rsq_f32_e32 v139, v138
	v_or_b32_e32 v138, s39, v152
	v_mul_f32_e32 v171, 0x45800000, v139
	v_cndmask_b32_e32 v139, v139, v171, vcc
	v_mul_f32_e32 v98, v98, v139
	v_fma_f32 v98, v129, v98, v145
	v_fmac_f32_e32 v98, v120, v186
	v_mul_f32_e32 v98, v100, v98
	v_cvt_pk_bf16_f32 v98, v98, s0
	global_store_short v[90:91], v98, off
	v_mul_f32_e32 v98, v99, v139
	v_fma_f32 v98, v142, v98, v146
	v_fmac_f32_e32 v98, v120, v187
	v_mul_f32_e32 v96, v96, v98
	v_cvt_pk_bf16_f32 v96, v96, s0
	global_store_short v[90:91], v96, off offset:32
	v_mul_f32_e32 v96, v175, v139
	v_fma_f32 v96, v143, v96, v147
	v_fmac_f32_e32 v96, v120, v140
	v_mul_f32_e32 v92, v92, v96
	v_cvt_pk_bf16_f32 v92, v92, s0
	global_store_short v[90:91], v92, off offset:64
	v_mul_f32_e32 v92, v174, v139
	v_fma_f32 v92, v144, v92, v148
	v_fmac_f32_e32 v92, v120, v141
	v_mul_f32_e32 v88, v88, v92
	v_cvt_pk_bf16_f32 v88, v88, s0
	v_ashrrev_i32_e32 v139, 31, v138
	global_store_short v[90:91], v88, off offset:96
	v_lshlrev_b64 v[90:91], 6, v[138:139]
	v_lshl_add_u64 v[90:91], v[130:131], 0, v[90:91]
	v_mul_f32_e32 v88, 0x4b800000, v170
	v_cmp_gt_f32_e32 vcc, s38, v170
	v_lshlrev_b32_e32 v92, 16, v182
	v_lshlrev_b64 v[98:99], 11, v[138:139]
	v_cndmask_b32_e32 v88, v170, v88, vcc
	v_rsq_f32_e32 v88, v88
	v_lshl_add_u64 v[98:99], v[132:133], 0, v[98:99]
	v_or_b32_e32 v100, s39, v153
	v_mfma_f32_16x16x32_bf16 v[138:141], v[102:105], v[28:31], v[164:167]
	v_mul_f32_e32 v96, 0x45800000, v88
	v_cndmask_b32_e32 v88, v88, v96, vcc
	v_add_u32_e32 v120, 0xb400, v162
	v_mfma_f32_16x16x32_bf16 v[102:105], v[102:105], v[8:11], v[108:111]
	v_add_u32_e32 v166, 0xbc00, v162
	s_waitcnt vmcnt(9)
	v_add_f32_e32 v90, v252, v253
	global_load_dwordx2 v[252:253], v[250:251], off offset:1088
	v_mul_f32_e32 v91, v94, v88
	v_fma_f32 v91, v129, v91, v145
	v_fmac_f32_e32 v91, v90, v92
	v_mul_f32_e32 v91, v101, v91
	v_cvt_pk_bf16_f32 v91, v91, s0
	v_mul_f32_e32 v92, v95, v88
	global_store_short v[98:99], v91, off
	v_lshlrev_b32_e32 v91, 16, v183
	v_fma_f32 v92, v142, v92, v146
	v_fmac_f32_e32 v92, v90, v91
	v_mul_f32_e32 v91, v97, v92
	v_cvt_pk_bf16_f32 v91, v91, s0
	v_mul_f32_e32 v92, v169, v88
	global_store_short v[98:99], v91, off offset:32
	v_lshlrev_b32_e32 v91, 16, v184
	v_fma_f32 v92, v143, v92, v147
	v_fmac_f32_e32 v92, v90, v91
	v_mul_f32_e32 v91, v93, v92
	v_cvt_pk_bf16_f32 v91, v91, s0
	v_mul_f32_e32 v88, v168, v88
	global_store_short v[98:99], v91, off offset:64
	v_lshlrev_b32_e32 v91, 16, v185
	v_fma_f32 v88, v144, v88, v148
	v_fmac_f32_e32 v88, v90, v91
	v_mul_f32_e32 v88, v89, v88
	v_cvt_pk_bf16_f32 v88, v88, s0
	v_ashrrev_i32_e32 v101, 31, v100
	global_store_short v[98:99], v88, off offset:96
	v_lshlrev_b64 v[88:89], 6, v[100:101]
	v_lshl_add_u64 v[88:89], v[130:131], 0, v[88:89]
	ds_read_b128 v[92:95], v157 offset:6656
	ds_read_b128 v[96:99], v157 offset:6720
	v_mfma_f32_16x16x32_bf16 v[108:111], v[84:87], v[44:47], v[116:119]
	ds_read_u16 v167, v161 offset:28400
	ds_read_u16 v168, v161 offset:28432
	ds_read_u16 v169, v161 offset:28464
	ds_read_u16 v170, v161 offset:28496
	ds_read_u16 v171, v161 offset:29440
	ds_read_u16 v172, v161 offset:29472
	ds_read_u16 v173, v161 offset:29504
	ds_read_u16 v174, v161 offset:29536
	ds_read2_b32 v[116:117], v120 offset1:16
	v_lshlrev_b64 v[100:101], 11, v[100:101]
	s_waitcnt lgkmcnt(7)
	v_lshlrev_b32_e32 v168, 16, v168
	v_mfma_f32_16x16x32_bf16 v[88:91], v[84:87], v[64:67], v[112:115]
	s_waitcnt lgkmcnt(0)
	v_add_f32_e32 v175, 0, v116
	v_add_f32_e32 v175, v175, v117
	v_mfma_f32_16x16x32_bf16 v[112:115], v[84:87], v[24:27], v[138:141]
	ds_read2_b32 v[118:119], v120 offset0:32 offset1:48
	s_nop 1
	ds_read2_b32 v[138:139], v166 offset0:4 offset1:20
	ds_read2_b32 v[140:141], v166 offset0:36 offset1:52
	v_lshlrev_b32_e32 v120, 16, v167
	s_waitcnt lgkmcnt(2)
; __device__ __forceinline__ float bf2f(bf16_t b) { return __uint_as_float(((unsigned)b) << 16); }
; __device__ __forceinline__ void post_phase(PREF p, char* smem, const int wid_u, const int tile_first, const int tile_end, const int tile_step) {
;     ...
; #pragma unroll
;     for (int mt = 0; mt < 2; ++mt)
; #pragma unroll
;       for (int jj = 0; jj < 4; ++jj) {
;         const int tok = mt * 16 + fq * 4 + jj, row = row0 + tok;
;         float yv[4], sm_ = 0.f;
; #pragma unroll
;         for (int nt = 0; nt < 4; ++nt) { yv[nt] = ys[tok * 516 + w * 64 + nt * 16 + fr]; sm_ += yv[nt]; }
;         const float mean = row16_sum(sm_) * (1.f / 64.f);
;         float vs = 0.f;
; #pragma unroll
;         for (int nt = 0; nt < 4; ++nt) { yv[nt] -= mean; vs += yv[nt] * yv[nt]; }
;         const float rs = rsqrtf(row16_sum(vs) * (1.f / 64.f) + 64e-5f);
;         const float2 sb2 = *(const float2*)(P_SBON + ((size_t)row * 8 + w) * 2);
;         const float sbs = sb2.x + sb2.y;
; #pragma unroll
;         for (int nt = 0; nt < 4; ++nt) {
;           const float vv = bf2f(vt[tok * 520 + w * 64 + nt * 16 + fr]);
;           const float o = (yv[nt] * rs * lng[nt] + lnb[nt] + sbs * vv) * acc[mt][nt][jj];
;           mo[(size_t)row * D + 512 + w * 64 + nt * 16 + fr] = (bf16_t)(cvt_pk_bf16(o, 0.f) & 0xffff);
;         }
;       }
	v_mov_b32_e32 v167, v118
	v_mfma_f32_16x16x32_bf16 v[84:87], v[84:87], v[4:7], v[102:105]
	s_waitcnt lgkmcnt(1)
	v_add_f32_e32 v176, 0, v138
	v_add_f32_e32 v118, v175, v118
	v_mov_b32_e32 v166, v119
	v_lshl_add_u64 v[104:105], v[132:133], 0, v[100:101]
	v_mfma_f32_16x16x32_bf16 v[100:103], v[92:95], v[40:43], v[108:111]
	v_mfma_f32_16x16x32_bf16 v[108:111], v[92:95], v[20:23], v[112:115]
	s_nop 2
	v_add_f32_e32 v112, v176, v139
	s_waitcnt lgkmcnt(0)
	v_add_f32_e32 v175, v112, v140
	v_mfma_f32_16x16x32_bf16 v[112:115], v[92:95], v[0:3], v[84:87]
	s_nop 2
	v_add_f32_e32 v84, v118, v119
	v_mfma_f32_16x16x32_bf16 v[88:91], v[92:95], v[60:63], v[88:91]
	v_add_f32_e32 v85, v175, v141
	v_add_f32_dpp v84, v84, v84 row_ror:8 row_mask:0xf bank_mask:0xf bound_ctrl:1
	s_waitcnt vmcnt(9)
	v_add_f32_e32 v119, v254, v255
	global_load_dwordx2 v[254:255], v[250:251], off offset:1152
	v_add_f32_dpp v84, v84, v84 row_ror:4 row_mask:0xf bank_mask:0xf bound_ctrl:1
	v_add_f32_dpp v118, v85, v85 row_ror:8 row_mask:0xf bank_mask:0xf bound_ctrl:1
	v_mfma_f32_16x16x32_bf16 v[88:91], v[96:99], v[80:83], v[88:91]
	v_add_f32_dpp v84, v84, v84 row_ror:2 row_mask:0xf bank_mask:0xf bound_ctrl:1
	s_nop 1
	v_add_f32_dpp v84, v84, v84 row_ror:1 row_mask:0xf bank_mask:0xf bound_ctrl:1
	v_mfma_f32_16x16x32_bf16 v[92:95], v[96:99], v[80:83], v[100:103]
	s_nop 2
	v_mul_f32_e32 v100, 0x3c800000, v84
	v_mfma_f32_16x16x32_bf16 v[84:87], v[96:99], v[80:83], v[108:111]
	v_add_f32_e64 v102, v116, -v100
	v_add_f32_e64 v103, v117, -v100
	v_pk_add_f32 v[100:101], v[166:167], v[100:101] op_sel_hi:[1,0] neg_lo:[0,1] neg_hi:[0,1]
	v_mfma_f32_16x16x32_bf16 v[80:83], v[96:99], v[80:83], v[112:115]
	v_add_f32_dpp v96, v118, v118 row_ror:4 row_mask:0xf bank_mask:0xf bound_ctrl:1
	v_pk_mul_f32 v[108:109], v[102:103], v[102:103]
	v_pk_mul_f32 v[110:111], v[100:101], v[100:101]
	v_add_f32_dpp v96, v96, v96 row_ror:2 row_mask:0xf bank_mask:0xf bound_ctrl:1
	v_mov_b32_e32 v114, v141
	v_mov_b32_e32 v115, v140
	v_add_f32_dpp v96, v96, v96 row_ror:1 row_mask:0xf bank_mask:0xf bound_ctrl:1
	v_mul_f32_e32 v96, 0x3c800000, v96
	v_pk_add_f32 v[98:99], v[138:139], v[96:97] op_sel_hi:[1,0] neg_lo:[0,1] neg_hi:[0,1]
	v_pk_add_f32 v[96:97], v[114:115], v[96:97] op_sel_hi:[1,0] neg_lo:[0,1] neg_hi:[0,1]
	v_pk_mul_f32 v[112:113], v[98:99], v[98:99]
	v_pk_mul_f32 v[114:115], v[96:97], v[96:97]
	v_mov_b32_e32 v116, v112
	v_mov_b32_e32 v117, v108
	v_mov_b32_e32 v108, v113
	v_pk_add_f32 v[108:109], v[116:117], v[108:109]
	v_mov_b32_e32 v112, v115
	v_mov_b32_e32 v113, v111
	v_pk_add_f32 v[108:109], v[112:113], v[108:109]
	v_mov_b32_e32 v115, v110
	v_pk_add_f32 v[108:109], v[114:115], v[108:109]
	v_mov_b32_e32 v111, v121
	v_mov_b32_e32 v110, v121
	v_lshlrev_b32_e32 v112, 16, v170
	v_mov_b32_dpp v111, v109 row_ror:8 row_mask:0xf bank_mask:0xf
	v_mov_b32_dpp v110, v108 row_ror:8 row_mask:0xf bank_mask:0xf
	v_pk_add_f32 v[108:109], v[108:109], v[110:111]
	v_mov_b32_e32 v111, v121
	v_mov_b32_e32 v110, v121
	s_nop 0
	v_mov_b32_dpp v111, v109 row_ror:4 row_mask:0xf bank_mask:0xf
	v_mov_b32_dpp v110, v108 row_ror:4 row_mask:0xf bank_mask:0xf
	v_pk_add_f32 v[108:109], v[108:109], v[110:111]
	v_mov_b32_e32 v111, v121
	v_mov_b32_e32 v110, v121
	s_nop 0
	v_mov_b32_dpp v111, v109 row_ror:2 row_mask:0xf bank_mask:0xf
	v_mov_b32_dpp v110, v108 row_ror:2 row_mask:0xf bank_mask:0xf
	v_pk_add_f32 v[108:109], v[108:109], v[110:111]
	v_mov_b32_e32 v111, v121
	v_mov_b32_e32 v110, v121
	s_nop 0
	v_mov_b32_dpp v111, v109 row_ror:1 row_mask:0xf bank_mask:0xf
	v_mov_b32_dpp v110, v108 row_ror:1 row_mask:0xf bank_mask:0xf
	v_pk_add_f32 v[108:109], v[108:109], v[110:111]
	v_lshlrev_b32_e32 v111, 16, v169
	v_pk_fma_f32 v[108:109], v[108:109], s[16:17], v[106:107] op_sel_hi:[1,0,0]
	s_nop 0
	v_mul_f32_e32 v110, 0x4b800000, v109
	v_cmp_gt_f32_e32 vcc, s38, v109
	s_nop 1
	v_cndmask_b32_e32 v109, v109, v110, vcc
	v_rsq_f32_e32 v109, v109
	v_or_b32_e32 v110, s39, v154
	v_mul_f32_e32 v113, 0x45800000, v109
	v_cndmask_b32_e32 v109, v109, v113, vcc
	v_mul_f32_e32 v102, v102, v109
	v_fma_f32 v102, v129, v102, v145
	v_fmac_f32_e32 v102, v119, v120
	v_mul_f32_e32 v88, v88, v102
	v_cvt_pk_bf16_f32 v88, v88, s0
	global_store_short v[104:105], v88, off
	v_mul_f32_e32 v88, v103, v109
	v_fma_f32 v88, v142, v88, v146
	v_fmac_f32_e32 v88, v119, v168
	v_mul_f32_e32 v88, v92, v88
	v_cvt_pk_bf16_f32 v88, v88, s0
	global_store_short v[104:105], v88, off offset:32
	v_mul_f32_e32 v88, v101, v109
	v_fma_f32 v88, v143, v88, v147
	v_fmac_f32_e32 v88, v119, v111
	v_mul_f32_e32 v84, v84, v88
	v_cvt_pk_bf16_f32 v84, v84, s0
	global_store_short v[104:105], v84, off offset:64
	v_mul_f32_e32 v84, v100, v109
	v_fma_f32 v84, v144, v84, v148
	v_fmac_f32_e32 v84, v119, v112
	v_mul_f32_e32 v80, v80, v84
	v_ashrrev_i32_e32 v111, 31, v110
	v_cvt_pk_bf16_f32 v80, v80, s0
	v_lshlrev_b64 v[100:101], 6, v[110:111]
	global_store_short v[104:105], v80, off offset:96
	v_lshl_add_u64 v[100:101], v[130:131], 0, v[100:101]
	v_mul_f32_e32 v80, 0x4b800000, v108
	v_cmp_gt_f32_e32 vcc, s38, v108
	v_lshlrev_b32_e32 v88, 16, v171
	v_lshlrev_b64 v[102:103], 11, v[110:111]
	v_cndmask_b32_e32 v80, v108, v80, vcc
	v_rsq_f32_e32 v80, v80
	s_nop 0
	v_mul_f32_e32 v84, 0x45800000, v80
	v_cndmask_b32_e32 v80, v80, v84, vcc
	v_mul_f32_e32 v92, v98, v80
	v_fma_f32 v92, v129, v92, v145
	v_add_u32_e32 v98, 0xcc00, v162
	s_waitcnt vmcnt(9)
; __device__ __forceinline__ float bf2f(bf16_t b) { return __uint_as_float(((unsigned)b) << 16); }
; __device__ __forceinline__ void post_phase(PREF p, char* smem, const int wid_u, const int tile_first, const int tile_end, const int tile_step) {
;     ...
; #pragma unroll
;     for (int mt = 0; mt < 2; ++mt)
; #pragma unroll
;       for (int jj = 0; jj < 4; ++jj) {
;         const int tok = mt * 16 + fq * 4 + jj, row = row0 + tok;
;         float yv[4], sm_ = 0.f;
; #pragma unroll
;         for (int nt = 0; nt < 4; ++nt) { yv[nt] = ys[tok * 516 + w * 64 + nt * 16 + fr]; sm_ += yv[nt]; }
;         const float mean = row16_sum(sm_) * (1.f / 64.f);
;         float vs = 0.f;
; #pragma unroll
;         for (int nt = 0; nt < 4; ++nt) { yv[nt] -= mean; vs += yv[nt] * yv[nt]; }
;         const float rs = rsqrtf(row16_sum(vs) * (1.f / 64.f) + 64e-5f);
;         const float2 sb2 = *(const float2*)(P_SBON + ((size_t)row * 8 + w) * 2);
;         const float sbs = sb2.x + sb2.y;
; #pragma unroll
;         for (int nt = 0; nt < 4; ++nt) {
;           const float vv = bf2f(vt[tok * 520 + w * 64 + nt * 16 + fr]);
;           const float o = (yv[nt] * rs * lng[nt] + lnb[nt] + sbs * vv) * acc[mt][nt][jj];
;           mo[(size_t)row * D + 512 + w * 64 + nt * 16 + fr] = (bf16_t)(cvt_pk_bf16(o, 0.f) & 0xffff);
;         }
;       }
	v_add_f32_e32 v84, v252, v253
	global_load_dwordx2 v[252:253], v[250:251], off offset:1216
	v_fmac_f32_e32 v92, v84, v88
	v_mul_f32_e32 v88, v89, v92
	v_lshl_add_u64 v[100:101], v[132:133], 0, v[102:103]
	v_cvt_pk_bf16_f32 v88, v88, s0
	v_mul_f32_e32 v89, v99, v80
	global_store_short v[100:101], v88, off
	v_lshlrev_b32_e32 v88, 16, v172
	v_fma_f32 v89, v142, v89, v146
	v_fmac_f32_e32 v89, v84, v88
	v_mul_f32_e32 v88, v93, v89
	v_cvt_pk_bf16_f32 v88, v88, s0
	v_mul_f32_e32 v89, v97, v80
	global_store_short v[100:101], v88, off offset:32
	v_lshlrev_b32_e32 v88, 16, v173
	v_fma_f32 v89, v143, v89, v147
	v_fmac_f32_e32 v89, v84, v88
	v_mul_f32_e32 v85, v85, v89
	v_cvt_pk_bf16_f32 v85, v85, s0
	v_mul_f32_e32 v80, v96, v80
	global_store_short v[100:101], v85, off offset:64
	v_lshlrev_b32_e32 v85, 16, v174
	v_fma_f32 v80, v144, v80, v148
	v_fmac_f32_e32 v80, v84, v85
	v_mul_f32_e32 v80, v81, v80
	v_cvt_pk_bf16_f32 v80, v80, s0
	global_store_short v[100:101], v80, off offset:96
	v_or_b32_e32 v80, s39, v155
	v_ashrrev_i32_e32 v81, 31, v80
	v_lshlrev_b64 v[84:85], 6, v[80:81]
	v_lshl_add_u64 v[84:85], v[130:131], 0, v[84:85]
	v_add_u32_e32 v92, 0xc400, v162
	ds_read_u16 v100, v161 offset:30480
	ds_read_u16 v101, v161 offset:30512
	ds_read_u16 v112, v161 offset:30544
	ds_read_u16 v113, v161 offset:30576
	ds_read_u16 v114, v161 offset:31520
	ds_read_u16 v115, v161 offset:31552
	ds_read_u16 v116, v161 offset:31584
	ds_read_u16 v117, v161 offset:31616
	ds_read2_b32 v[88:89], v92 offset0:8 offset1:24
	ds_read2_b32 v[92:93], v92 offset0:40 offset1:56
	ds_read2_b32 v[96:97], v98 offset0:12 offset1:28
	ds_read2_b32 v[98:99], v98 offset0:44 offset1:60
	s_waitcnt lgkmcnt(10)
	v_lshlrev_b32_e32 v119, 16, v101
	s_waitcnt lgkmcnt(3)
	v_add_f32_e32 v104, 0, v88
	v_add_f32_e32 v104, v104, v89
	s_waitcnt lgkmcnt(1)
	v_add_f32_e32 v105, 0, v96
	v_add_f32_e32 v105, v105, v97
	v_mov_b32_e32 v101, v92
	s_waitcnt lgkmcnt(0)
	v_mov_b32_e32 v103, v98
	v_add_f32_e32 v92, v104, v92
	v_add_f32_e32 v98, v105, v98
	v_lshlrev_b32_e32 v118, 16, v100
	v_mov_b32_e32 v100, v93
	v_add_f32_e32 v92, v92, v93
	v_add_f32_e32 v93, v98, v99
	v_mov_b32_e32 v102, v99
	v_add_f32_dpp v92, v92, v92 row_ror:8 row_mask:0xf bank_mask:0xf bound_ctrl:1
	v_add_f32_dpp v93, v93, v93 row_ror:8 row_mask:0xf bank_mask:0xf bound_ctrl:1
	v_lshlrev_b64 v[80:81], 11, v[80:81]
	v_add_f32_dpp v92, v92, v92 row_ror:4 row_mask:0xf bank_mask:0xf bound_ctrl:1
	v_add_f32_dpp v93, v93, v93 row_ror:4 row_mask:0xf bank_mask:0xf bound_ctrl:1
	v_lshl_add_u64 v[80:81], v[132:133], 0, v[80:81]
	v_add_f32_dpp v92, v92, v92 row_ror:2 row_mask:0xf bank_mask:0xf bound_ctrl:1
	v_add_f32_dpp v93, v93, v93 row_ror:2 row_mask:0xf bank_mask:0xf bound_ctrl:1
	s_nop 0
	v_add_f32_dpp v92, v92, v92 row_ror:1 row_mask:0xf bank_mask:0xf bound_ctrl:1
	v_add_f32_dpp v93, v93, v93 row_ror:1 row_mask:0xf bank_mask:0xf bound_ctrl:1
	v_mul_f32_e32 v92, 0x3c800000, v92
	v_mul_f32_e32 v98, 0x3c800000, v93
	v_pk_add_f32 v[88:89], v[88:89], v[92:93] op_sel_hi:[1,0] neg_lo:[0,1] neg_hi:[0,1]
	v_pk_add_f32 v[96:97], v[96:97], v[98:99] op_sel_hi:[1,0] neg_lo:[0,1] neg_hi:[0,1]
	v_pk_add_f32 v[92:93], v[100:101], v[92:93] op_sel_hi:[1,0] neg_lo:[0,1] neg_hi:[0,1]
	v_pk_add_f32 v[98:99], v[102:103], v[98:99] op_sel_hi:[1,0] neg_lo:[0,1] neg_hi:[0,1]
	v_pk_mul_f32 v[100:101], v[88:89], v[88:89]
	v_pk_mul_f32 v[104:105], v[96:97], v[96:97]
	v_pk_mul_f32 v[102:103], v[92:93], v[92:93]
	v_pk_mul_f32 v[108:109], v[98:99], v[98:99]
	v_mov_b32_e32 v110, v104
	v_mov_b32_e32 v111, v100
	v_mov_b32_e32 v100, v105
	s_waitcnt vmcnt(9)
; __device__ __forceinline__ float bf2f(bf16_t b) { return __uint_as_float(((unsigned)b) << 16); }
; __device__ __forceinline__ void post_phase(PREF p, char* smem, const int wid_u, const int tile_first, const int tile_end, const int tile_step) {
;     ...
; #pragma unroll
;     for (int mt = 0; mt < 2; ++mt)
; #pragma unroll
;       for (int jj = 0; jj < 4; ++jj) {
;         const int tok = mt * 16 + fq * 4 + jj, row = row0 + tok;
;         float yv[4], sm_ = 0.f;
; #pragma unroll
;         for (int nt = 0; nt < 4; ++nt) { yv[nt] = ys[tok * 516 + w * 64 + nt * 16 + fr]; sm_ += yv[nt]; }
;         const float mean = row16_sum(sm_) * (1.f / 64.f);
;         float vs = 0.f;
; #pragma unroll
;         for (int nt = 0; nt < 4; ++nt) { yv[nt] -= mean; vs += yv[nt] * yv[nt]; }
;         const float rs = rsqrtf(row16_sum(vs) * (1.f / 64.f) + 64e-5f);
;         const float2 sb2 = *(const float2*)(P_SBON + ((size_t)row * 8 + w) * 2);
;         const float sbs = sb2.x + sb2.y;
; #pragma unroll
;         for (int nt = 0; nt < 4; ++nt) {
;           const float vv = bf2f(vt[tok * 520 + w * 64 + nt * 16 + fr]);
;           const float o = (yv[nt] * rs * lng[nt] + lnb[nt] + sbs * vv) * acc[mt][nt][jj];
;           mo[(size_t)row * D + 512 + w * 64 + nt * 16 + fr] = (bf16_t)(cvt_pk_bf16(o, 0.f) & 0xffff);
;         }
;       }
	v_add_f32_e32 v104, v254, v255
	v_pk_add_f32 v[84:85], v[110:111], v[100:101]
	v_mov_b32_e32 v100, v109
	v_mov_b32_e32 v101, v103
	v_pk_add_f32 v[84:85], v[100:101], v[84:85]
	v_mov_b32_e32 v109, v102
	v_pk_add_f32 v[84:85], v[108:109], v[84:85]
	v_mov_b32_e32 v101, v121
	v_mov_b32_e32 v100, v121
	v_lshlrev_b32_e32 v102, 16, v113
	v_mov_b32_dpp v101, v85 row_ror:8 row_mask:0xf bank_mask:0xf
	v_mov_b32_dpp v100, v84 row_ror:8 row_mask:0xf bank_mask:0xf
	v_pk_add_f32 v[84:85], v[84:85], v[100:101]
	v_mov_b32_e32 v101, v121
	v_mov_b32_e32 v100, v121
	s_nop 0
	v_mov_b32_dpp v101, v85 row_ror:4 row_mask:0xf bank_mask:0xf
	v_mov_b32_dpp v100, v84 row_ror:4 row_mask:0xf bank_mask:0xf
	v_pk_add_f32 v[84:85], v[84:85], v[100:101]
	v_mov_b32_e32 v101, v121
	v_mov_b32_e32 v100, v121
	s_nop 0
	v_mov_b32_dpp v101, v85 row_ror:2 row_mask:0xf bank_mask:0xf
	v_mov_b32_dpp v100, v84 row_ror:2 row_mask:0xf bank_mask:0xf
	v_pk_add_f32 v[84:85], v[84:85], v[100:101]
	v_mov_b32_e32 v101, v121
	v_mov_b32_e32 v100, v121
	s_nop 0
	v_mov_b32_dpp v101, v85 row_ror:1 row_mask:0xf bank_mask:0xf
	v_mov_b32_dpp v100, v84 row_ror:1 row_mask:0xf bank_mask:0xf
	v_pk_add_f32 v[84:85], v[84:85], v[100:101]
	v_lshlrev_b32_e32 v101, 16, v112
	v_pk_fma_f32 v[84:85], v[84:85], s[16:17], v[106:107] op_sel_hi:[1,0,0]
	s_add_i32 s17, s17, s42
	v_mul_f32_e32 v100, 0x4b800000, v85
	v_cmp_gt_f32_e32 vcc, s38, v85
	s_cmpk_gt_i32 s17, 0xbff
	s_nop 0
	v_cndmask_b32_e32 v85, v85, v100, vcc
	v_rsq_f32_e32 v85, v85
	v_or_b32_e32 v100, s39, v156
	v_mul_f32_e32 v103, 0x45800000, v85
	v_cndmask_b32_e32 v85, v85, v103, vcc
	v_mul_f32_e32 v88, v88, v85
	v_fma_f32 v88, v129, v88, v145
	v_fmac_f32_e32 v88, v104, v118
	v_mul_f32_e32 v88, v90, v88
	v_cvt_pk_bf16_f32 v88, v88, s0
	global_store_short v[80:81], v88, off
	v_mul_f32_e32 v88, v89, v85
	v_fma_f32 v88, v142, v88, v146
	v_fmac_f32_e32 v88, v104, v119
	v_mul_f32_e32 v88, v94, v88
	v_cvt_pk_bf16_f32 v88, v88, s0
	global_store_short v[80:81], v88, off offset:32
	v_mul_f32_e32 v88, v93, v85
	v_mul_f32_e32 v85, v92, v85
	v_fma_f32 v88, v143, v88, v147
	v_fma_f32 v85, v144, v85, v148
	v_fmac_f32_e32 v88, v104, v101
	v_fmac_f32_e32 v85, v104, v102
	v_mul_f32_e32 v86, v86, v88
	v_mul_f32_e32 v82, v82, v85
	v_cvt_pk_bf16_f32 v86, v86, s0
	v_cvt_pk_bf16_f32 v82, v82, s0
	v_ashrrev_i32_e32 v101, 31, v100
	global_store_short v[80:81], v86, off offset:64
	global_store_short v[80:81], v82, off offset:96
	v_lshlrev_b64 v[80:81], 6, v[100:101]
	v_lshl_add_u64 v[80:81], v[130:131], 0, v[80:81]
	v_mul_f32_e32 v82, 0x4b800000, v84
	v_cmp_gt_f32_e32 vcc, s38, v84
	v_lshlrev_b32_e32 v85, 16, v115
	v_lshlrev_b64 v[88:89], 11, v[100:101]
	v_cndmask_b32_e32 v82, v84, v82, vcc
	v_rsq_f32_e32 v82, v82
	v_lshlrev_b32_e32 v84, 16, v114
	v_lshl_add_u64 v[88:89], v[132:133], 0, v[88:89]
	v_lshlrev_b32_e32 v86, 16, v116
	v_mul_f32_e32 v90, 0x45800000, v82
	v_cndmask_b32_e32 v82, v82, v90, vcc
	v_mul_f32_e32 v90, v96, v82
	v_mul_f32_e32 v92, v97, v82
	v_fma_f32 v90, v129, v90, v145
	v_fma_f32 v92, v142, v92, v146
	s_waitcnt vmcnt(8)
	v_add_f32_e32 v80, v252, v253
	v_fmac_f32_e32 v90, v80, v84
	v_fmac_f32_e32 v92, v80, v85
	v_mul_f32_e32 v81, v91, v90
	v_mul_f32_e32 v84, v95, v92
	v_cvt_pk_bf16_f32 v81, v81, s0
	v_cvt_pk_bf16_f32 v84, v84, s0
	global_store_short v[88:89], v81, off
	global_store_short v[88:89], v84, off offset:32
	v_mul_f32_e32 v81, v99, v82
	v_fma_f32 v81, v143, v81, v147
	v_fmac_f32_e32 v81, v80, v86
	v_mul_f32_e32 v81, v87, v81
	v_cvt_pk_bf16_f32 v81, v81, s0
	v_mul_f32_e32 v82, v98, v82
	global_store_short v[88:89], v81, off offset:64
	v_lshlrev_b32_e32 v81, 16, v117
	v_fma_f32 v82, v144, v82, v148
	v_fmac_f32_e32 v82, v80, v81
	v_mul_f32_e32 v80, v83, v82
	v_cvt_pk_bf16_f32 v80, v80, s0
	global_store_short v[88:89], v80, off offset:96
	s_barrier
	s_cbranch_scc1 .LBB0_846

; #define LAS __attribute__((address_space(3)))
; __device__ __forceinline__ unsigned xb_add(unsigned* p, unsigned v) { return __hip_atomic_fetch_add(p, v, __ATOMIC_RELAXED, __HIP_MEMORY_SCOPE_AGENT); }
; __device__ __forceinline__ unsigned xb_xcc_id() { return (unsigned)__builtin_amdgcn_s_getreg((3 << 11) | 20) & 0xFu; }
; #define RUN_PHASE(PH) do { KP kp = kp0; asm volatile("" : "+s"(kp)); do_phase(*kp, PH, dyn_smem, wid_u); \
;     if (PH == 0) grid.sync(); \
;     else if (PH + 1 < NPHASE) xcd_barrier(*kp, (volatile LAS unsigned*)((LAS char*)dyn_smem + (SMEM_BYTES - 16)), wid_u); } while (0)
; __global__ void __launch_bounds__(NTHR, 2) mega_kernel(Params p) {
;   cg::grid_group grid = cg::this_grid();
;   const int wid_u = __builtin_amdgcn_readfirstlane(threadIdx.x >> 6);
;   typedef const __attribute__((address_space(4))) Params* KP;
;   const KP kp0 = (KP)__builtin_amdgcn_kernarg_segment_ptr();
;   volatile LAS unsigned* st = (volatile LAS unsigned*)((LAS char*)dyn_smem + (SMEM_BYTES - 16));
;   if (threadIdx.x < 2) st[threadIdx.x] = 0u;
;   __syncthreads();
;   if (threadIdx.x == 0) (void)xb_add(&((unsigned*)(kp0->ws + OFF_BAR))[XB_XCNT(xb_xcc_id())], 1u);
;     ...
;   RUN_PHASE(0); RUN_PHASE(1); RUN_PHASE(2); RUN_PHASE(3); RUN_PHASE(4); RUN_PHASE(5); RUN_PHASE(6);
;   RUN_PHASE(7); RUN_PHASE(8); RUN_PHASE(9); RUN_PHASE(10); RUN_PHASE(11); RUN_PHASE(12); RUN_PHASE(13);
;     ...
; }
	.amdhsa_kernel _Z11mega_kernel6Params
		.amdhsa_group_segment_fixed_size 0
		.amdhsa_private_segment_fixed_size 0
		.amdhsa_kernarg_size 536
		.amdhsa_user_sgpr_count 2
		.amdhsa_user_sgpr_dispatch_ptr 0
		.amdhsa_user_sgpr_queue_ptr 0
		.amdhsa_user_sgpr_kernarg_segment_ptr 1
		.amdhsa_user_sgpr_dispatch_id 0
		.amdhsa_user_sgpr_kernarg_preload_length 0
		.amdhsa_user_sgpr_kernarg_preload_offset 0
		.amdhsa_user_sgpr_private_segment_size 0
		.amdhsa_uses_dynamic_stack 0
		.amdhsa_enable_private_segment 0
		.amdhsa_system_sgpr_workgroup_id_x 1
		.amdhsa_system_sgpr_workgroup_id_y 0
		.amdhsa_system_sgpr_workgroup_id_z 0
		.amdhsa_system_sgpr_workgroup_info 0
		.amdhsa_system_vgpr_workitem_id 2
		.amdhsa_next_free_vgpr 256
		.amdhsa_next_free_sgpr 98
		.amdhsa_accum_offset 256
		.amdhsa_reserve_vcc 1
		.amdhsa_float_round_mode_32 0
		.amdhsa_float_round_mode_16_64 0
		.amdhsa_float_denorm_mode_32 3
		.amdhsa_float_denorm_mode_16_64 3
		.amdhsa_dx10_clamp 1
		.amdhsa_ieee_mode 1
		.amdhsa_fp16_overflow 0
		.amdhsa_tg_split 0
		.amdhsa_exception_fp_ieee_invalid_op 0
		.amdhsa_exception_fp_denorm_src 0
		.amdhsa_exception_fp_ieee_div_zero 0
		.amdhsa_exception_fp_ieee_overflow 0
		.amdhsa_exception_fp_ieee_underflow 0
		.amdhsa_exception_fp_ieee_inexact 0
		.amdhsa_exception_int_div_zero 0
	.end_amdhsa_kernel

; #define LAS __attribute__((address_space(3)))
; __device__ __forceinline__ unsigned xb_add(unsigned* p, unsigned v) { return __hip_atomic_fetch_add(p, v, __ATOMIC_RELAXED, __HIP_MEMORY_SCOPE_AGENT); }
; __device__ __forceinline__ unsigned xb_xcc_id() { return (unsigned)__builtin_amdgcn_s_getreg((3 << 11) | 20) & 0xFu; }
; #define RUN_PHASE(PH) do { KP kp = kp0; asm volatile("" : "+s"(kp)); do_phase(*kp, PH, dyn_smem, wid_u); \
;     if (PH == 0) grid.sync(); \
;     else if (PH + 1 < NPHASE) xcd_barrier(*kp, (volatile LAS unsigned*)((LAS char*)dyn_smem + (SMEM_BYTES - 16)), wid_u); } while (0)
; __global__ void __launch_bounds__(NTHR, 2) mega_kernel(Params p) {
;   cg::grid_group grid = cg::this_grid();
;   const int wid_u = __builtin_amdgcn_readfirstlane(threadIdx.x >> 6);
;   typedef const __attribute__((address_space(4))) Params* KP;
;   const KP kp0 = (KP)__builtin_amdgcn_kernarg_segment_ptr();
;   volatile LAS unsigned* st = (volatile LAS unsigned*)((LAS char*)dyn_smem + (SMEM_BYTES - 16));
;   if (threadIdx.x < 2) st[threadIdx.x] = 0u;
;   __syncthreads();
;   if (threadIdx.x == 0) (void)xb_add(&((unsigned*)(kp0->ws + OFF_BAR))[XB_XCNT(xb_xcc_id())], 1u);
;     ...
;   RUN_PHASE(0); RUN_PHASE(1); RUN_PHASE(2); RUN_PHASE(3); RUN_PHASE(4); RUN_PHASE(5); RUN_PHASE(6);
;   RUN_PHASE(7); RUN_PHASE(8); RUN_PHASE(9); RUN_PHASE(10); RUN_PHASE(11); RUN_PHASE(12); RUN_PHASE(13);
;     ...
; }
; __global__ void __launch_bounds__(NTHR, 2) phase_kernel(Params p, int ph) {
;   const int wid_u = __builtin_amdgcn_readfirstlane(threadIdx.x >> 6);
;   do_phase(*(const __attribute__((address_space(4))) Params*)__builtin_amdgcn_kernarg_segment_ptr(), ph, dyn_smem, wid_u);
; }
amdhsa.kernels:
  - .agpr_count:     0
    .args:
      - .offset:         0
        .size:           280
        .value_kind:     by_value
      - .offset:         280
        .size:           4
        .value_kind:     hidden_block_count_x
      - .offset:         284
        .size:           4
        .value_kind:     hidden_block_count_y
      - .offset:         288
        .size:           4
        .value_kind:     hidden_block_count_z
      - .offset:         292
        .size:           2
        .value_kind:     hidden_group_size_x
      - .offset:         294
        .size:           2
        .value_kind:     hidden_group_size_y
      - .offset:         296
        .size:           2
        .value_kind:     hidden_group_size_z
      - .offset:         298
        .size:           2
        .value_kind:     hidden_remainder_x
      - .offset:         300
        .size:           2
        .value_kind:     hidden_remainder_y
      - .offset:         302
        .size:           2
        .value_kind:     hidden_remainder_z
      - .offset:         320
        .size:           8
        .value_kind:     hidden_global_offset_x
      - .offset:         328
        .size:           8
        .value_kind:     hidden_global_offset_y
      - .offset:         336
        .size:           8
        .value_kind:     hidden_global_offset_z
      - .offset:         344
        .size:           2
        .value_kind:     hidden_grid_dims
      - .offset:         368
        .size:           8
        .value_kind:     hidden_multigrid_sync_arg
      - .offset:         400
        .size:           4
        .value_kind:     hidden_dynamic_lds_size
    .group_segment_fixed_size: 0
    .kernarg_segment_align: 8
    .kernarg_segment_size: 536
    .language:       OpenCL C
    .language_version:
      - 2
      - 0
    .max_flat_workgroup_size: 512
    .name:           _Z11mega_kernel6Params
    .private_segment_fixed_size: 0
    .sgpr_count:     104
    .sgpr_spill_count: 7
    .symbol:         _Z11mega_kernel6Params.kd
    .uniform_work_group_size: 1
    .uses_dynamic_stack: false
    .vgpr_count:     256
    .vgpr_spill_count: 0
    .wavefront_size: 64
  - .agpr_count:     0
    .args:
      - .offset:         0
        .size:           280
        .value_kind:     by_value
      - .offset:         280
        .size:           4
        .value_kind:     by_value
      - .offset:         288
        .size:           4
        .value_kind:     hidden_block_count_x
      - .offset:         292
        .size:           4
        .value_kind:     hidden_block_count_y
      - .offset:         296
        .size:           4
        .value_kind:     hidden_block_count_z
      - .offset:         300
        .size:           2
        .value_kind:     hidden_group_size_x
      - .offset:         302
        .size:           2
        .value_kind:     hidden_group_size_y
      - .offset:         304
        .size:           2
        .value_kind:     hidden_group_size_z
      - .offset:         306
        .size:           2
        .value_kind:     hidden_remainder_x
      - .offset:         308
        .size:           2
        .value_kind:     hidden_remainder_y
      - .offset:         310
        .size:           2
        .value_kind:     hidden_remainder_z
      - .offset:         328
        .size:           8
        .value_kind:     hidden_global_offset_x
      - .offset:         336
        .size:           8
        .value_kind:     hidden_global_offset_y
      - .offset:         344
        .size:           8
        .value_kind:     hidden_global_offset_z
      - .offset:         352
        .size:           2
        .value_kind:     hidden_grid_dims
      - .offset:         408
        .size:           4
        .value_kind:     hidden_dynamic_lds_size
    .group_segment_fixed_size: 0
    .kernarg_segment_align: 8
    .kernarg_segment_size: 544
    .language:       OpenCL C
    .language_version:
      - 2
      - 0
    .max_flat_workgroup_size: 512
    .name:           _Z12phase_kernel6Paramsi
    .private_segment_fixed_size: 0
    .sgpr_count:     106
    .sgpr_spill_count: 0
    .symbol:         _Z12phase_kernel6Paramsi.kd
    .uniform_work_group_size: 1
    .uses_dynamic_stack: false
    .vgpr_count:     254
    .vgpr_spill_count: 0
    .wavefront_size: 64
